# in-place residual epilogues (out, dnL0b, dnL1a): each group's store issued right after its cvt (counted vmcnt over mixed loads+stores)
# baseline (speedup 1.0000x reference)
; __device__ __forceinline__ unsigned cvt_pk_bf16(float lo, float hi) { unsigned r; asm("v_cvt_pk_bf16_f32 %0, %1, %2" : "=v"(r) : "v"(lo), "v"(hi)); return r; }
;     __device__ __forceinline__ void operator()(const Acc& acc, const Unit& u, int wr, int wc, int fr, int fq) const {
;         const bool isx = u.pm < 128; const int mb = isx ? (u.pm >> 4) : 8;
;         const size_t tile0 = (size_t)(isx ? u.pm : u.pm - 128) * 256 * D;
;         const float* sp32 = (const float*)(isx ? srcx : srcc) + tile0; const bf16_t* sp16 = (const bf16_t*)(isx ? srcx : srcc) + tile0;
;         float* dp32 = (float*)(isx ? dstx : dstc) + tile0; bf16_t* dp16 = (bf16_t*)(isx ? dstx : dstc) + tile0;
;         const int r0 = wr * 64 + fr, col0 = u.pn * 256 + wc * 32 + 8 * fq; const float* gp = gate + (size_t)mb * 9216 + col0;
;         f32x4 gv[2][2];
; #pragma unroll
;         for (int bj = 0; bj < 2; ++bj)
; #pragma unroll
;             for (int n = 0; n < 2; ++n) gv[bj][n] = *(const f32x4*)(gp + bj * 128 + n * 4) * f;
; #pragma unroll
;         for (int ai = 0; ai < 2; ++ai)
; #pragma unroll
;             for (int m = 0; m < 4; ++m) { const size_t off = (size_t)(r0 + ai * 128 + m * 16) * D + col0;
; #pragma unroll
;                 for (int bj = 0; bj < 2; ++bj) { const size_t o2 = off + bj * 128; f32x4 s0, s1;
;                     if (SRC32) { s0 = *(const f32x4*)(sp32 + o2); s1 = *(const f32x4*)(sp32 + o2 + 4); }
;                     else { const u32x4 q = *(const u32x4*)(sp16 + o2); s0 = (f32x4){bf2f(q.x & 0xffffu), bf2f(q.x >> 16), bf2f(q.y & 0xffffu), bf2f(q.y >> 16)}; s1 = (f32x4){bf2f(q.z & 0xffffu), bf2f(q.z >> 16), bf2f(q.w & 0xffffu), bf2f(q.w >> 16)}; }
;                     const f32x4 v0 = s0 + gv[bj][0] * acc[ai][bj][m][0], v1 = s1 + gv[bj][1] * acc[ai][bj][m][1];
;                     if (DST32) { *(f32x4*)(dp32 + o2) = v0; *(f32x4*)(dp32 + o2 + 4) = v1; }
;                     else { u32x4 w; w.x = cvt_pk_bf16(v0.x, v0.y); w.y = cvt_pk_bf16(v0.z, v0.w); w.z = cvt_pk_bf16(v1.x, v1.y); w.w = cvt_pk_bf16(v1.z, v1.w); *(u32x4*)(dp16 + o2) = w; } } }
.LBB0_923:
	s_add_i32 s23, s40, 0xffffff80
	s_and_b64 s[44:45], s[44:45], exec
	s_cselect_b32 s40, s40, s23
	s_ashr_i32 s41, s40, 31
	v_lshl_or_b32 v238, s34, 8, v199
	s_lshl_b64 s[34:35], s[42:43], 2
	s_add_u32 s42, s52, s34
	s_addc_u32 s43, s53, s35
	v_lshlrev_b32_e32 v196, 2, v238
	global_load_dwordx4 v[128:131], v196, s[42:43]
	global_load_dwordx4 v[132:135], v196, s[42:43] offset:16
	global_load_dwordx4 v[136:139], v196, s[42:43] offset:512
	global_load_dwordx4 v[140:143], v196, s[42:43] offset:528
	s_lshl_b64 s[34:35], s[40:41], 19
	s_add_u32 s40, s86, s34
	s_addc_u32 s41, s87, s35
	v_lshl_add_u32 v197, v238, 1, v164
	global_load_dwordx4 v[144:147], v197, s[40:41]
	global_load_dwordx4 v[148:151], v197, s[40:41] offset:256
	v_lshl_add_u32 v196, v238, 1, v174
	global_load_dwordx4 v[152:155], v196, s[40:41]
	global_load_dwordx4 v[156:159], v196, s[40:41] offset:256
	v_lshl_add_u32 v197, v238, 1, v176
	global_load_dwordx4 v[188:191], v197, s[40:41]
	global_load_dwordx4 v[208:211], v197, s[40:41] offset:256
	v_lshl_add_u32 v196, v238, 1, v178
	global_load_dwordx4 v[212:215], v196, s[40:41]
	global_load_dwordx4 v[216:219], v196, s[40:41] offset:256
	v_lshl_add_u32 v197, v238, 1, v166
	global_load_dwordx4 v[220:223], v197, s[40:41]
	global_load_dwordx4 v[224:227], v197, s[40:41] offset:256
	v_lshl_add_u32 v196, v238, 1, v168
	global_load_dwordx4 v[228:231], v196, s[40:41]
	global_load_dwordx4 v[232:235], v196, s[40:41] offset:256
	s_waitcnt vmcnt(11)
	v_lshlrev_b32_e32 v192, 16, v144
	v_and_b32_e32 v193, 0xffff0000, v144
	v_lshlrev_b32_e32 v194, 16, v145
	v_and_b32_e32 v195, 0xffff0000, v145
	v_lshlrev_b32_e32 v144, 16, v146
	v_and_b32_e32 v145, 0xffff0000, v146
	v_lshlrev_b32_e32 v146, 16, v147
	v_and_b32_e32 v147, 0xffff0000, v147
	v_pk_fma_f32 v[124:125], v[124:125], v[128:129], v[192:193]
	v_pk_fma_f32 v[126:127], v[126:127], v[130:131], v[194:195]
	v_pk_fma_f32 v[120:121], v[120:121], v[132:133], v[144:145]
	v_pk_fma_f32 v[122:123], v[122:123], v[134:135], v[146:147]
	v_cvt_pk_bf16_f32 v124, v124, v125
	v_cvt_pk_bf16_f32 v125, v126, v127
	v_cvt_pk_bf16_f32 v126, v120, v121
	v_cvt_pk_bf16_f32 v127, v122, v123
	v_lshl_add_u32 v239, v238, 1, v164
	global_store_dwordx4 v239, v[124:127], s[40:41]
	s_waitcnt vmcnt(11)
	v_lshlrev_b32_e32 v192, 16, v148
	v_and_b32_e32 v193, 0xffff0000, v148
	v_lshlrev_b32_e32 v194, 16, v149
	v_and_b32_e32 v195, 0xffff0000, v149
	v_lshlrev_b32_e32 v148, 16, v150
	v_and_b32_e32 v149, 0xffff0000, v150
	v_lshlrev_b32_e32 v150, 16, v151
	v_and_b32_e32 v151, 0xffff0000, v151
	v_pk_fma_f32 v[108:109], v[108:109], v[136:137], v[192:193]
	v_pk_fma_f32 v[110:111], v[110:111], v[138:139], v[194:195]
	v_pk_fma_f32 v[104:105], v[104:105], v[140:141], v[148:149]
	v_pk_fma_f32 v[106:107], v[106:107], v[142:143], v[150:151]
	v_cvt_pk_bf16_f32 v108, v108, v109
	v_cvt_pk_bf16_f32 v109, v110, v111
	v_cvt_pk_bf16_f32 v110, v104, v105
	v_cvt_pk_bf16_f32 v111, v106, v107
	global_store_dwordx4 v239, v[108:111], s[40:41] offset:256
	s_waitcnt vmcnt(11)
	v_lshlrev_b32_e32 v192, 16, v152
	v_and_b32_e32 v193, 0xffff0000, v152
	v_lshlrev_b32_e32 v194, 16, v153
	v_and_b32_e32 v195, 0xffff0000, v153
	v_lshlrev_b32_e32 v152, 16, v154
	v_and_b32_e32 v153, 0xffff0000, v154
	v_lshlrev_b32_e32 v154, 16, v155
	v_and_b32_e32 v155, 0xffff0000, v155
	v_pk_fma_f32 v[116:117], v[116:117], v[128:129], v[192:193]
	v_pk_fma_f32 v[118:119], v[118:119], v[130:131], v[194:195]
	v_pk_fma_f32 v[112:113], v[112:113], v[132:133], v[152:153]
	v_pk_fma_f32 v[114:115], v[114:115], v[134:135], v[154:155]
	v_cvt_pk_bf16_f32 v116, v116, v117
	v_cvt_pk_bf16_f32 v117, v118, v119
	v_cvt_pk_bf16_f32 v118, v112, v113
	v_cvt_pk_bf16_f32 v119, v114, v115
	v_lshl_add_u32 v239, v238, 1, v174
	global_store_dwordx4 v239, v[116:119], s[40:41]
	s_waitcnt vmcnt(11)
	v_lshlrev_b32_e32 v192, 16, v156
	v_and_b32_e32 v193, 0xffff0000, v156
	v_lshlrev_b32_e32 v194, 16, v157
	v_and_b32_e32 v195, 0xffff0000, v157
	v_lshlrev_b32_e32 v156, 16, v158
	v_and_b32_e32 v157, 0xffff0000, v158
	v_lshlrev_b32_e32 v158, 16, v159
	v_and_b32_e32 v159, 0xffff0000, v159
	v_pk_fma_f32 v[100:101], v[100:101], v[136:137], v[192:193]
	v_pk_fma_f32 v[102:103], v[102:103], v[138:139], v[194:195]
	v_pk_fma_f32 v[96:97], v[96:97], v[140:141], v[156:157]
	v_pk_fma_f32 v[98:99], v[98:99], v[142:143], v[158:159]
	v_cvt_pk_bf16_f32 v100, v100, v101
	v_cvt_pk_bf16_f32 v101, v102, v103
	v_cvt_pk_bf16_f32 v102, v96, v97
	v_cvt_pk_bf16_f32 v103, v98, v99
	global_store_dwordx4 v239, v[100:103], s[40:41] offset:256
	v_lshl_add_u32 v197, v238, 1, v170
	global_load_dwordx4 v[144:147], v197, s[40:41]
	global_load_dwordx4 v[148:151], v197, s[40:41] offset:256
	v_lshl_add_u32 v196, v238, 1, v172
	global_load_dwordx4 v[152:155], v196, s[40:41]
	global_load_dwordx4 v[156:159], v196, s[40:41] offset:256
	s_waitcnt vmcnt(15)
	v_lshlrev_b32_e32 v192, 16, v188
	v_and_b32_e32 v193, 0xffff0000, v188
	v_lshlrev_b32_e32 v194, 16, v189
	v_and_b32_e32 v195, 0xffff0000, v189
	v_lshlrev_b32_e32 v188, 16, v190
	v_and_b32_e32 v189, 0xffff0000, v190
	v_lshlrev_b32_e32 v190, 16, v191
	v_and_b32_e32 v191, 0xffff0000, v191
	v_pk_fma_f32 v[92:93], v[92:93], v[128:129], v[192:193]
	v_pk_fma_f32 v[94:95], v[94:95], v[130:131], v[194:195]
	v_pk_fma_f32 v[88:89], v[88:89], v[132:133], v[188:189]
	v_pk_fma_f32 v[90:91], v[90:91], v[134:135], v[190:191]
	v_cvt_pk_bf16_f32 v92, v92, v93
	v_cvt_pk_bf16_f32 v93, v94, v95
	v_cvt_pk_bf16_f32 v94, v88, v89
	v_cvt_pk_bf16_f32 v95, v90, v91
	v_lshl_add_u32 v239, v238, 1, v176
	global_store_dwordx4 v239, v[92:95], s[40:41]
	s_waitcnt vmcnt(15)
; __device__ __forceinline__ unsigned cvt_pk_bf16(float lo, float hi) { unsigned r; asm("v_cvt_pk_bf16_f32 %0, %1, %2" : "=v"(r) : "v"(lo), "v"(hi)); return r; }
;     __device__ __forceinline__ void operator()(const Acc& acc, const Unit& u, int wr, int wc, int fr, int fq) const {
;     ...
;             for (int m = 0; m < 4; ++m) { const size_t off = (size_t)(r0 + ai * 128 + m * 16) * D + col0;
; #pragma unroll
;                 for (int bj = 0; bj < 2; ++bj) { const size_t o2 = off + bj * 128; f32x4 s0, s1;
;                     if (SRC32) { s0 = *(const f32x4*)(sp32 + o2); s1 = *(const f32x4*)(sp32 + o2 + 4); }
;                     else { const u32x4 q = *(const u32x4*)(sp16 + o2); s0 = (f32x4){bf2f(q.x & 0xffffu), bf2f(q.x >> 16), bf2f(q.y & 0xffffu), bf2f(q.y >> 16)}; s1 = (f32x4){bf2f(q.z & 0xffffu), bf2f(q.z >> 16), bf2f(q.w & 0xffffu), bf2f(q.w >> 16)}; }
;                     const f32x4 v0 = s0 + gv[bj][0] * acc[ai][bj][m][0], v1 = s1 + gv[bj][1] * acc[ai][bj][m][1];
;                     if (DST32) { *(f32x4*)(dp32 + o2) = v0; *(f32x4*)(dp32 + o2 + 4) = v1; }
;                     else { u32x4 w; w.x = cvt_pk_bf16(v0.x, v0.y); w.y = cvt_pk_bf16(v0.z, v0.w); w.z = cvt_pk_bf16(v1.x, v1.y); w.w = cvt_pk_bf16(v1.z, v1.w); *(u32x4*)(dp16 + o2) = w; } } }
	v_lshlrev_b32_e32 v192, 16, v208
	v_and_b32_e32 v193, 0xffff0000, v208
	v_lshlrev_b32_e32 v194, 16, v209
	v_and_b32_e32 v195, 0xffff0000, v209
	v_lshlrev_b32_e32 v208, 16, v210
	v_and_b32_e32 v209, 0xffff0000, v210
	v_lshlrev_b32_e32 v210, 16, v211
	v_and_b32_e32 v211, 0xffff0000, v211
	v_pk_fma_f32 v[84:85], v[84:85], v[136:137], v[192:193]
	v_pk_fma_f32 v[86:87], v[86:87], v[138:139], v[194:195]
	v_pk_fma_f32 v[80:81], v[80:81], v[140:141], v[208:209]
	v_pk_fma_f32 v[82:83], v[82:83], v[142:143], v[210:211]
	v_cvt_pk_bf16_f32 v84, v84, v85
	v_cvt_pk_bf16_f32 v85, v86, v87
	v_cvt_pk_bf16_f32 v86, v80, v81
	v_cvt_pk_bf16_f32 v87, v82, v83
	global_store_dwordx4 v239, v[84:87], s[40:41] offset:256
	s_waitcnt vmcnt(15)
	v_lshlrev_b32_e32 v192, 16, v212
	v_and_b32_e32 v193, 0xffff0000, v212
	v_lshlrev_b32_e32 v194, 16, v213
	v_and_b32_e32 v195, 0xffff0000, v213
	v_lshlrev_b32_e32 v212, 16, v214
	v_and_b32_e32 v213, 0xffff0000, v214
	v_lshlrev_b32_e32 v214, 16, v215
	v_and_b32_e32 v215, 0xffff0000, v215
	v_pk_fma_f32 v[76:77], v[76:77], v[128:129], v[192:193]
	v_pk_fma_f32 v[78:79], v[78:79], v[130:131], v[194:195]
	v_pk_fma_f32 v[72:73], v[72:73], v[132:133], v[212:213]
	v_pk_fma_f32 v[74:75], v[74:75], v[134:135], v[214:215]
	v_cvt_pk_bf16_f32 v76, v76, v77
	v_cvt_pk_bf16_f32 v77, v78, v79
	v_cvt_pk_bf16_f32 v78, v72, v73
	v_cvt_pk_bf16_f32 v79, v74, v75
	v_lshl_add_u32 v239, v238, 1, v178
	global_store_dwordx4 v239, v[76:79], s[40:41]
	s_waitcnt vmcnt(15)
	v_lshlrev_b32_e32 v192, 16, v216
	v_and_b32_e32 v193, 0xffff0000, v216
	v_lshlrev_b32_e32 v194, 16, v217
	v_and_b32_e32 v195, 0xffff0000, v217
	v_lshlrev_b32_e32 v216, 16, v218
	v_and_b32_e32 v217, 0xffff0000, v218
	v_lshlrev_b32_e32 v218, 16, v219
	v_and_b32_e32 v219, 0xffff0000, v219
	v_pk_fma_f32 v[68:69], v[68:69], v[136:137], v[192:193]
	v_pk_fma_f32 v[70:71], v[70:71], v[138:139], v[194:195]
	v_pk_fma_f32 v[64:65], v[64:65], v[140:141], v[216:217]
	v_pk_fma_f32 v[66:67], v[66:67], v[142:143], v[218:219]
	v_cvt_pk_bf16_f32 v68, v68, v69
	v_cvt_pk_bf16_f32 v69, v70, v71
	v_cvt_pk_bf16_f32 v70, v64, v65
	v_cvt_pk_bf16_f32 v71, v66, v67
	global_store_dwordx4 v239, v[68:71], s[40:41] offset:256
	s_waitcnt vmcnt(15)
	v_lshlrev_b32_e32 v192, 16, v220
	v_and_b32_e32 v193, 0xffff0000, v220
	v_lshlrev_b32_e32 v194, 16, v221
	v_and_b32_e32 v195, 0xffff0000, v221
	v_lshlrev_b32_e32 v220, 16, v222
	v_and_b32_e32 v221, 0xffff0000, v222
	v_lshlrev_b32_e32 v222, 16, v223
	v_and_b32_e32 v223, 0xffff0000, v223
	v_pk_fma_f32 v[60:61], v[60:61], v[128:129], v[192:193]
	v_pk_fma_f32 v[62:63], v[62:63], v[130:131], v[194:195]
	v_pk_fma_f32 v[56:57], v[56:57], v[132:133], v[220:221]
	v_pk_fma_f32 v[58:59], v[58:59], v[134:135], v[222:223]
	v_cvt_pk_bf16_f32 v60, v60, v61
	v_cvt_pk_bf16_f32 v61, v62, v63
	v_cvt_pk_bf16_f32 v62, v56, v57
	v_cvt_pk_bf16_f32 v63, v58, v59
	v_lshl_add_u32 v239, v238, 1, v166
	global_store_dwordx4 v239, v[60:63], s[40:41]
	s_waitcnt vmcnt(15)
	v_lshlrev_b32_e32 v192, 16, v224
	v_and_b32_e32 v193, 0xffff0000, v224
	v_lshlrev_b32_e32 v194, 16, v225
	v_and_b32_e32 v195, 0xffff0000, v225
	v_lshlrev_b32_e32 v224, 16, v226
	v_and_b32_e32 v225, 0xffff0000, v226
	v_lshlrev_b32_e32 v226, 16, v227
	v_and_b32_e32 v227, 0xffff0000, v227
	v_pk_fma_f32 v[52:53], v[52:53], v[136:137], v[192:193]
	v_pk_fma_f32 v[54:55], v[54:55], v[138:139], v[194:195]
	v_pk_fma_f32 v[48:49], v[48:49], v[140:141], v[224:225]
	v_pk_fma_f32 v[50:51], v[50:51], v[142:143], v[226:227]
	v_cvt_pk_bf16_f32 v52, v52, v53
	v_cvt_pk_bf16_f32 v53, v54, v55
	v_cvt_pk_bf16_f32 v54, v48, v49
	v_cvt_pk_bf16_f32 v55, v50, v51
	global_store_dwordx4 v239, v[52:55], s[40:41] offset:256
	s_waitcnt vmcnt(15)
	v_lshlrev_b32_e32 v192, 16, v228
	v_and_b32_e32 v193, 0xffff0000, v228
	v_lshlrev_b32_e32 v194, 16, v229
	v_and_b32_e32 v195, 0xffff0000, v229
	v_lshlrev_b32_e32 v228, 16, v230
	v_and_b32_e32 v229, 0xffff0000, v230
	v_lshlrev_b32_e32 v230, 16, v231
	v_and_b32_e32 v231, 0xffff0000, v231
	v_pk_fma_f32 v[44:45], v[44:45], v[128:129], v[192:193]
	v_pk_fma_f32 v[46:47], v[46:47], v[130:131], v[194:195]
	v_pk_fma_f32 v[40:41], v[40:41], v[132:133], v[228:229]
	v_pk_fma_f32 v[42:43], v[42:43], v[134:135], v[230:231]
	v_cvt_pk_bf16_f32 v44, v44, v45
	v_cvt_pk_bf16_f32 v45, v46, v47
	v_cvt_pk_bf16_f32 v46, v40, v41
	v_cvt_pk_bf16_f32 v47, v42, v43
	v_lshl_add_u32 v239, v238, 1, v168
	global_store_dwordx4 v239, v[44:47], s[40:41]
	s_waitcnt vmcnt(15)
; __device__ __forceinline__ unsigned cvt_pk_bf16(float lo, float hi) { unsigned r; asm("v_cvt_pk_bf16_f32 %0, %1, %2" : "=v"(r) : "v"(lo), "v"(hi)); return r; }
; #define PG8_BAR __builtin_amdgcn_s_barrier()
; template <class Epi, class Sched, bool SWAPD = false>
; __device__ __forceinline__ void gemm_phase(LAS unsigned char* lds, const Gemm g, const Sched& S, const Epi& E) {
;     ...
;         cur = nxt; cA = nA; cB = nB; ++ui;
;         if (wr == 1) PG8_BAR;
;     __device__ __forceinline__ void operator()(const Acc& acc, const Unit& u, int wr, int wc, int fr, int fq) const {
;     ...
;             for (int m = 0; m < 4; ++m) { const size_t off = (size_t)(r0 + ai * 128 + m * 16) * D + col0;
; #pragma unroll
;                 for (int bj = 0; bj < 2; ++bj) { const size_t o2 = off + bj * 128; f32x4 s0, s1;
;                     if (SRC32) { s0 = *(const f32x4*)(sp32 + o2); s1 = *(const f32x4*)(sp32 + o2 + 4); }
;                     else { const u32x4 q = *(const u32x4*)(sp16 + o2); s0 = (f32x4){bf2f(q.x & 0xffffu), bf2f(q.x >> 16), bf2f(q.y & 0xffffu), bf2f(q.y >> 16)}; s1 = (f32x4){bf2f(q.z & 0xffffu), bf2f(q.z >> 16), bf2f(q.w & 0xffffu), bf2f(q.w >> 16)}; }
;                     const f32x4 v0 = s0 + gv[bj][0] * acc[ai][bj][m][0], v1 = s1 + gv[bj][1] * acc[ai][bj][m][1];
;                     if (DST32) { *(f32x4*)(dp32 + o2) = v0; *(f32x4*)(dp32 + o2 + 4) = v1; }
;                     else { u32x4 w; w.x = cvt_pk_bf16(v0.x, v0.y); w.y = cvt_pk_bf16(v0.z, v0.w); w.z = cvt_pk_bf16(v1.x, v1.y); w.w = cvt_pk_bf16(v1.z, v1.w); *(u32x4*)(dp16 + o2) = w; } } }
	v_lshlrev_b32_e32 v192, 16, v232
	v_and_b32_e32 v193, 0xffff0000, v232
	v_lshlrev_b32_e32 v194, 16, v233
	v_and_b32_e32 v195, 0xffff0000, v233
	v_lshlrev_b32_e32 v232, 16, v234
	v_and_b32_e32 v233, 0xffff0000, v234
	v_lshlrev_b32_e32 v234, 16, v235
	v_and_b32_e32 v235, 0xffff0000, v235
	v_pk_fma_f32 v[28:29], v[28:29], v[136:137], v[192:193]
	v_pk_fma_f32 v[30:31], v[30:31], v[138:139], v[194:195]
	v_pk_fma_f32 v[24:25], v[24:25], v[140:141], v[232:233]
	v_pk_fma_f32 v[26:27], v[26:27], v[142:143], v[234:235]
	v_cvt_pk_bf16_f32 v28, v28, v29
	v_cvt_pk_bf16_f32 v29, v30, v31
	v_cvt_pk_bf16_f32 v30, v24, v25
	v_cvt_pk_bf16_f32 v31, v26, v27
	global_store_dwordx4 v239, v[28:31], s[40:41] offset:256
	s_waitcnt vmcnt(11)
	v_lshlrev_b32_e32 v192, 16, v144
	v_and_b32_e32 v193, 0xffff0000, v144
	v_lshlrev_b32_e32 v194, 16, v145
	v_and_b32_e32 v195, 0xffff0000, v145
	v_lshlrev_b32_e32 v144, 16, v146
	v_and_b32_e32 v145, 0xffff0000, v146
	v_lshlrev_b32_e32 v146, 16, v147
	v_and_b32_e32 v147, 0xffff0000, v147
	v_pk_fma_f32 v[36:37], v[36:37], v[128:129], v[192:193]
	v_pk_fma_f32 v[38:39], v[38:39], v[130:131], v[194:195]
	v_pk_fma_f32 v[32:33], v[32:33], v[132:133], v[144:145]
	v_pk_fma_f32 v[34:35], v[34:35], v[134:135], v[146:147]
	v_cvt_pk_bf16_f32 v36, v36, v37
	v_cvt_pk_bf16_f32 v37, v38, v39
	v_cvt_pk_bf16_f32 v38, v32, v33
	v_cvt_pk_bf16_f32 v39, v34, v35
	v_lshl_add_u32 v239, v238, 1, v170
	global_store_dwordx4 v239, v[36:39], s[40:41]
	s_waitcnt vmcnt(11)
	v_lshlrev_b32_e32 v192, 16, v148
	v_and_b32_e32 v193, 0xffff0000, v148
	v_lshlrev_b32_e32 v194, 16, v149
	v_and_b32_e32 v195, 0xffff0000, v149
	v_lshlrev_b32_e32 v148, 16, v150
	v_and_b32_e32 v149, 0xffff0000, v150
	v_lshlrev_b32_e32 v150, 16, v151
	v_and_b32_e32 v151, 0xffff0000, v151
	v_pk_fma_f32 v[12:13], v[12:13], v[136:137], v[192:193]
	v_pk_fma_f32 v[14:15], v[14:15], v[138:139], v[194:195]
	v_pk_fma_f32 v[8:9], v[8:9], v[140:141], v[148:149]
	v_pk_fma_f32 v[10:11], v[10:11], v[142:143], v[150:151]
	v_cvt_pk_bf16_f32 v12, v12, v13
	v_cvt_pk_bf16_f32 v13, v14, v15
	v_cvt_pk_bf16_f32 v14, v8, v9
	v_cvt_pk_bf16_f32 v15, v10, v11
	global_store_dwordx4 v239, v[12:15], s[40:41] offset:256
	s_waitcnt vmcnt(11)
	v_lshlrev_b32_e32 v192, 16, v152
	v_and_b32_e32 v193, 0xffff0000, v152
	v_lshlrev_b32_e32 v194, 16, v153
	v_and_b32_e32 v195, 0xffff0000, v153
	v_lshlrev_b32_e32 v152, 16, v154
	v_and_b32_e32 v153, 0xffff0000, v154
	v_lshlrev_b32_e32 v154, 16, v155
	v_and_b32_e32 v155, 0xffff0000, v155
	v_pk_fma_f32 v[20:21], v[20:21], v[128:129], v[192:193]
	v_pk_fma_f32 v[22:23], v[22:23], v[130:131], v[194:195]
	v_pk_fma_f32 v[16:17], v[16:17], v[132:133], v[152:153]
	v_pk_fma_f32 v[18:19], v[18:19], v[134:135], v[154:155]
	v_cvt_pk_bf16_f32 v20, v20, v21
	v_cvt_pk_bf16_f32 v21, v22, v23
	v_cvt_pk_bf16_f32 v22, v16, v17
	v_cvt_pk_bf16_f32 v23, v18, v19
	v_lshl_add_u32 v239, v238, 1, v172
	global_store_dwordx4 v239, v[20:23], s[40:41]
	s_waitcnt vmcnt(11)
	v_lshlrev_b32_e32 v192, 16, v156
	v_and_b32_e32 v193, 0xffff0000, v156
	v_lshlrev_b32_e32 v194, 16, v157
	v_and_b32_e32 v195, 0xffff0000, v157
	v_lshlrev_b32_e32 v156, 16, v158
	v_and_b32_e32 v157, 0xffff0000, v158
	v_lshlrev_b32_e32 v158, 16, v159
	v_and_b32_e32 v159, 0xffff0000, v159
	v_pk_fma_f32 v[4:5], v[4:5], v[136:137], v[192:193]
	v_pk_fma_f32 v[6:7], v[6:7], v[138:139], v[194:195]
	v_pk_fma_f32 v[0:1], v[0:1], v[140:141], v[156:157]
	v_pk_fma_f32 v[2:3], v[2:3], v[142:143], v[158:159]
	v_cvt_pk_bf16_f32 v4, v4, v5
	v_cvt_pk_bf16_f32 v5, v6, v7
	v_cvt_pk_bf16_f32 v6, v0, v1
	v_cvt_pk_bf16_f32 v7, v2, v3
	global_store_dwordx4 v239, v[4:7], s[40:41] offset:256
	s_andn2_b64 vcc, exec, s[4:5]
	s_mov_b64 s[4:5], -1
	s_cbranch_vccnz .LBB0_910
	s_andn2_b64 vcc, exec, s[8:9]
	s_cbranch_vccnz .LBB0_909
	s_barrier
	s_branch .LBB0_909

; __device__ __forceinline__ unsigned cvt_pk_bf16(float lo, float hi) { unsigned r; asm("v_cvt_pk_bf16_f32 %0, %1, %2" : "=v"(r) : "v"(lo), "v"(hi)); return r; }
;     __device__ __forceinline__ void operator()(const Acc& acc, const Unit& u, int wr, int wc, int fr, int fq) const {
;         const bool isx = u.pm < 128; const int mb = isx ? (u.pm >> 4) : 8;
;         const size_t tile0 = (size_t)(isx ? u.pm : u.pm - 128) * 256 * D;
;         const float* sp32 = (const float*)(isx ? srcx : srcc) + tile0; const bf16_t* sp16 = (const bf16_t*)(isx ? srcx : srcc) + tile0;
;         float* dp32 = (float*)(isx ? dstx : dstc) + tile0; bf16_t* dp16 = (bf16_t*)(isx ? dstx : dstc) + tile0;
;         const int r0 = wr * 64 + fr, col0 = u.pn * 256 + wc * 32 + 8 * fq; const float* gp = gate + (size_t)mb * 9216 + col0;
;         f32x4 gv[2][2];
; #pragma unroll
;         for (int bj = 0; bj < 2; ++bj)
; #pragma unroll
;             for (int n = 0; n < 2; ++n) gv[bj][n] = *(const f32x4*)(gp + bj * 128 + n * 4) * f;
; #pragma unroll
;         for (int ai = 0; ai < 2; ++ai)
; #pragma unroll
;             for (int m = 0; m < 4; ++m) { const size_t off = (size_t)(r0 + ai * 128 + m * 16) * D + col0;
; #pragma unroll
;                 for (int bj = 0; bj < 2; ++bj) { const size_t o2 = off + bj * 128; f32x4 s0, s1;
;                     if (SRC32) { s0 = *(const f32x4*)(sp32 + o2); s1 = *(const f32x4*)(sp32 + o2 + 4); }
;                     else { const u32x4 q = *(const u32x4*)(sp16 + o2); s0 = (f32x4){bf2f(q.x & 0xffffu), bf2f(q.x >> 16), bf2f(q.y & 0xffffu), bf2f(q.y >> 16)}; s1 = (f32x4){bf2f(q.z & 0xffffu), bf2f(q.z >> 16), bf2f(q.w & 0xffffu), bf2f(q.w >> 16)}; }
;                     const f32x4 v0 = s0 + gv[bj][0] * acc[ai][bj][m][0], v1 = s1 + gv[bj][1] * acc[ai][bj][m][1];
;                     if (DST32) { *(f32x4*)(dp32 + o2) = v0; *(f32x4*)(dp32 + o2 + 4) = v1; }
;                     else { u32x4 w; w.x = cvt_pk_bf16(v0.x, v0.y); w.y = cvt_pk_bf16(v0.z, v0.w); w.z = cvt_pk_bf16(v1.x, v1.y); w.w = cvt_pk_bf16(v1.z, v1.w); *(u32x4*)(dp16 + o2) = w; } } }
.LBB0_1126:
	s_add_i32 s38, s56, 0xffffff80
	s_and_b64 s[36:37], s[36:37], exec
	s_cselect_b32 s36, s56, s38
	s_ashr_i32 s37, s36, 31
	s_lshl_b64 s[34:35], s[34:35], 2
	v_lshl_or_b32 v238, s57, 8, v209
	s_add_u32 s34, s46, s34
	s_addc_u32 s35, s47, s35
	v_lshlrev_b32_e32 v234, 2, v238
	global_load_dwordx4 v[128:131], v234, s[34:35]
	global_load_dwordx4 v[132:135], v234, s[34:35] offset:16
	global_load_dwordx4 v[136:139], v234, s[34:35] offset:512
	global_load_dwordx4 v[140:143], v234, s[34:35] offset:528
	s_lshl_b64 s[34:35], s[36:37], 19
	s_add_u32 s34, s86, s34
	s_addc_u32 s35, s87, s35
	v_lshl_add_u32 v235, v238, 1, v164
	global_load_dwordx4 v[144:147], v235, s[34:35]
	global_load_dwordx4 v[148:151], v235, s[34:35] offset:256
	v_lshl_add_u32 v234, v238, 1, v174
	global_load_dwordx4 v[152:155], v234, s[34:35]
	global_load_dwordx4 v[156:159], v234, s[34:35] offset:256
	v_lshl_add_u32 v235, v238, 1, v176
	global_load_dwordx4 v[188:191], v235, s[34:35]
	global_load_dwordx4 v[192:195], v235, s[34:35] offset:256
	v_lshl_add_u32 v234, v238, 1, v178
	global_load_dwordx4 v[196:199], v234, s[34:35]
	global_load_dwordx4 v[200:203], v234, s[34:35] offset:256
	v_lshl_add_u32 v235, v238, 1, v166
	global_load_dwordx4 v[214:217], v235, s[34:35]
	global_load_dwordx4 v[218:221], v235, s[34:35] offset:256
	v_lshl_add_u32 v234, v238, 1, v168
	global_load_dwordx4 v[222:225], v234, s[34:35]
	global_load_dwordx4 v[226:229], v234, s[34:35] offset:256
	s_waitcnt vmcnt(11)
	v_pk_mul_f32 v[128:129], v[128:129], 0.5 op_sel_hi:[1,0]
	v_pk_mul_f32 v[130:131], v[130:131], 0.5 op_sel_hi:[1,0]
	v_pk_mul_f32 v[132:133], v[132:133], 0.5 op_sel_hi:[1,0]
	v_pk_mul_f32 v[134:135], v[134:135], 0.5 op_sel_hi:[1,0]
	v_pk_mul_f32 v[136:137], v[136:137], 0.5 op_sel_hi:[1,0]
	v_pk_mul_f32 v[138:139], v[138:139], 0.5 op_sel_hi:[1,0]
	v_pk_mul_f32 v[140:141], v[140:141], 0.5 op_sel_hi:[1,0]
	v_pk_mul_f32 v[142:143], v[142:143], 0.5 op_sel_hi:[1,0]
	v_lshlrev_b32_e32 v230, 16, v144
	v_and_b32_e32 v231, 0xffff0000, v144
	v_lshlrev_b32_e32 v232, 16, v145
	v_and_b32_e32 v233, 0xffff0000, v145
	v_lshlrev_b32_e32 v144, 16, v146
	v_and_b32_e32 v145, 0xffff0000, v146
	v_lshlrev_b32_e32 v146, 16, v147
	v_and_b32_e32 v147, 0xffff0000, v147
	v_pk_fma_f32 v[124:125], v[124:125], v[128:129], v[230:231]
	v_pk_fma_f32 v[126:127], v[126:127], v[130:131], v[232:233]
	v_pk_fma_f32 v[120:121], v[120:121], v[132:133], v[144:145]
	v_pk_fma_f32 v[122:123], v[122:123], v[134:135], v[146:147]
	v_cvt_pk_bf16_f32 v124, v124, v125
	v_cvt_pk_bf16_f32 v125, v126, v127
	v_cvt_pk_bf16_f32 v126, v120, v121
	v_cvt_pk_bf16_f32 v127, v122, v123
	v_lshl_add_u32 v239, v238, 1, v164
	global_store_dwordx4 v239, v[124:127], s[34:35]
	s_waitcnt vmcnt(11)
	v_lshlrev_b32_e32 v230, 16, v148
	v_and_b32_e32 v231, 0xffff0000, v148
	v_lshlrev_b32_e32 v232, 16, v149
	v_and_b32_e32 v233, 0xffff0000, v149
	v_lshlrev_b32_e32 v148, 16, v150
	v_and_b32_e32 v149, 0xffff0000, v150
	v_lshlrev_b32_e32 v150, 16, v151
	v_and_b32_e32 v151, 0xffff0000, v151
	v_pk_fma_f32 v[108:109], v[108:109], v[136:137], v[230:231]
	v_pk_fma_f32 v[110:111], v[110:111], v[138:139], v[232:233]
	v_pk_fma_f32 v[104:105], v[104:105], v[140:141], v[148:149]
	v_pk_fma_f32 v[106:107], v[106:107], v[142:143], v[150:151]
	v_cvt_pk_bf16_f32 v108, v108, v109
	v_cvt_pk_bf16_f32 v109, v110, v111
	v_cvt_pk_bf16_f32 v110, v104, v105
	v_cvt_pk_bf16_f32 v111, v106, v107
	global_store_dwordx4 v239, v[108:111], s[34:35] offset:256
	s_waitcnt vmcnt(11)
	v_lshlrev_b32_e32 v230, 16, v152
	v_and_b32_e32 v231, 0xffff0000, v152
	v_lshlrev_b32_e32 v232, 16, v153
	v_and_b32_e32 v233, 0xffff0000, v153
	v_lshlrev_b32_e32 v152, 16, v154
	v_and_b32_e32 v153, 0xffff0000, v154
	v_lshlrev_b32_e32 v154, 16, v155
	v_and_b32_e32 v155, 0xffff0000, v155
	v_pk_fma_f32 v[116:117], v[116:117], v[128:129], v[230:231]
	v_pk_fma_f32 v[118:119], v[118:119], v[130:131], v[232:233]
	v_pk_fma_f32 v[112:113], v[112:113], v[132:133], v[152:153]
	v_pk_fma_f32 v[114:115], v[114:115], v[134:135], v[154:155]
	v_cvt_pk_bf16_f32 v116, v116, v117
	v_cvt_pk_bf16_f32 v117, v118, v119
	v_cvt_pk_bf16_f32 v118, v112, v113
	v_cvt_pk_bf16_f32 v119, v114, v115
	v_lshl_add_u32 v239, v238, 1, v174
	global_store_dwordx4 v239, v[116:119], s[34:35]
	s_waitcnt vmcnt(11)
	v_lshlrev_b32_e32 v230, 16, v156
	v_and_b32_e32 v231, 0xffff0000, v156
	v_lshlrev_b32_e32 v232, 16, v157
	v_and_b32_e32 v233, 0xffff0000, v157
	v_lshlrev_b32_e32 v156, 16, v158
	v_and_b32_e32 v157, 0xffff0000, v158
	v_lshlrev_b32_e32 v158, 16, v159
	v_and_b32_e32 v159, 0xffff0000, v159
	v_pk_fma_f32 v[100:101], v[100:101], v[136:137], v[230:231]
	v_pk_fma_f32 v[102:103], v[102:103], v[138:139], v[232:233]
	v_pk_fma_f32 v[96:97], v[96:97], v[140:141], v[156:157]
	v_pk_fma_f32 v[98:99], v[98:99], v[142:143], v[158:159]
	v_cvt_pk_bf16_f32 v100, v100, v101
	v_cvt_pk_bf16_f32 v101, v102, v103
	v_cvt_pk_bf16_f32 v102, v96, v97
	v_cvt_pk_bf16_f32 v103, v98, v99
	global_store_dwordx4 v239, v[100:103], s[34:35] offset:256
	v_lshl_add_u32 v235, v238, 1, v170
	global_load_dwordx4 v[144:147], v235, s[34:35]
	global_load_dwordx4 v[148:151], v235, s[34:35] offset:256
	v_lshl_add_u32 v234, v238, 1, v172
	global_load_dwordx4 v[152:155], v234, s[34:35]
	global_load_dwordx4 v[156:159], v234, s[34:35] offset:256
	s_waitcnt vmcnt(15)
; __device__ __forceinline__ unsigned cvt_pk_bf16(float lo, float hi) { unsigned r; asm("v_cvt_pk_bf16_f32 %0, %1, %2" : "=v"(r) : "v"(lo), "v"(hi)); return r; }
;     __device__ __forceinline__ void operator()(const Acc& acc, const Unit& u, int wr, int wc, int fr, int fq) const {
;     ...
;             for (int m = 0; m < 4; ++m) { const size_t off = (size_t)(r0 + ai * 128 + m * 16) * D + col0;
; #pragma unroll
;                 for (int bj = 0; bj < 2; ++bj) { const size_t o2 = off + bj * 128; f32x4 s0, s1;
;                     if (SRC32) { s0 = *(const f32x4*)(sp32 + o2); s1 = *(const f32x4*)(sp32 + o2 + 4); }
;                     else { const u32x4 q = *(const u32x4*)(sp16 + o2); s0 = (f32x4){bf2f(q.x & 0xffffu), bf2f(q.x >> 16), bf2f(q.y & 0xffffu), bf2f(q.y >> 16)}; s1 = (f32x4){bf2f(q.z & 0xffffu), bf2f(q.z >> 16), bf2f(q.w & 0xffffu), bf2f(q.w >> 16)}; }
;                     const f32x4 v0 = s0 + gv[bj][0] * acc[ai][bj][m][0], v1 = s1 + gv[bj][1] * acc[ai][bj][m][1];
;                     if (DST32) { *(f32x4*)(dp32 + o2) = v0; *(f32x4*)(dp32 + o2 + 4) = v1; }
;                     else { u32x4 w; w.x = cvt_pk_bf16(v0.x, v0.y); w.y = cvt_pk_bf16(v0.z, v0.w); w.z = cvt_pk_bf16(v1.x, v1.y); w.w = cvt_pk_bf16(v1.z, v1.w); *(u32x4*)(dp16 + o2) = w; } } }
	v_lshlrev_b32_e32 v230, 16, v188
	v_and_b32_e32 v231, 0xffff0000, v188
	v_lshlrev_b32_e32 v232, 16, v189
	v_and_b32_e32 v233, 0xffff0000, v189
	v_lshlrev_b32_e32 v188, 16, v190
	v_and_b32_e32 v189, 0xffff0000, v190
	v_lshlrev_b32_e32 v190, 16, v191
	v_and_b32_e32 v191, 0xffff0000, v191
	v_pk_fma_f32 v[92:93], v[92:93], v[128:129], v[230:231]
	v_pk_fma_f32 v[94:95], v[94:95], v[130:131], v[232:233]
	v_pk_fma_f32 v[88:89], v[88:89], v[132:133], v[188:189]
	v_pk_fma_f32 v[90:91], v[90:91], v[134:135], v[190:191]
	v_cvt_pk_bf16_f32 v92, v92, v93
	v_cvt_pk_bf16_f32 v93, v94, v95
	v_cvt_pk_bf16_f32 v94, v88, v89
	v_cvt_pk_bf16_f32 v95, v90, v91
	v_lshl_add_u32 v239, v238, 1, v176
	global_store_dwordx4 v239, v[92:95], s[34:35]
	s_waitcnt vmcnt(15)
	v_lshlrev_b32_e32 v230, 16, v192
	v_and_b32_e32 v231, 0xffff0000, v192
	v_lshlrev_b32_e32 v232, 16, v193
	v_and_b32_e32 v233, 0xffff0000, v193
	v_lshlrev_b32_e32 v192, 16, v194
	v_and_b32_e32 v193, 0xffff0000, v194
	v_lshlrev_b32_e32 v194, 16, v195
	v_and_b32_e32 v195, 0xffff0000, v195
	v_pk_fma_f32 v[84:85], v[84:85], v[136:137], v[230:231]
	v_pk_fma_f32 v[86:87], v[86:87], v[138:139], v[232:233]
	v_pk_fma_f32 v[80:81], v[80:81], v[140:141], v[192:193]
	v_pk_fma_f32 v[82:83], v[82:83], v[142:143], v[194:195]
	v_cvt_pk_bf16_f32 v84, v84, v85
	v_cvt_pk_bf16_f32 v85, v86, v87
	v_cvt_pk_bf16_f32 v86, v80, v81
	v_cvt_pk_bf16_f32 v87, v82, v83
	global_store_dwordx4 v239, v[84:87], s[34:35] offset:256
	s_waitcnt vmcnt(15)
	v_lshlrev_b32_e32 v230, 16, v196
	v_and_b32_e32 v231, 0xffff0000, v196
	v_lshlrev_b32_e32 v232, 16, v197
	v_and_b32_e32 v233, 0xffff0000, v197
	v_lshlrev_b32_e32 v196, 16, v198
	v_and_b32_e32 v197, 0xffff0000, v198
	v_lshlrev_b32_e32 v198, 16, v199
	v_and_b32_e32 v199, 0xffff0000, v199
	v_pk_fma_f32 v[76:77], v[76:77], v[128:129], v[230:231]
	v_pk_fma_f32 v[78:79], v[78:79], v[130:131], v[232:233]
	v_pk_fma_f32 v[72:73], v[72:73], v[132:133], v[196:197]
	v_pk_fma_f32 v[74:75], v[74:75], v[134:135], v[198:199]
	v_cvt_pk_bf16_f32 v76, v76, v77
	v_cvt_pk_bf16_f32 v77, v78, v79
	v_cvt_pk_bf16_f32 v78, v72, v73
	v_cvt_pk_bf16_f32 v79, v74, v75
	v_lshl_add_u32 v239, v238, 1, v178
	global_store_dwordx4 v239, v[76:79], s[34:35]
	s_waitcnt vmcnt(15)
	v_lshlrev_b32_e32 v230, 16, v200
	v_and_b32_e32 v231, 0xffff0000, v200
	v_lshlrev_b32_e32 v232, 16, v201
	v_and_b32_e32 v233, 0xffff0000, v201
	v_lshlrev_b32_e32 v200, 16, v202
	v_and_b32_e32 v201, 0xffff0000, v202
	v_lshlrev_b32_e32 v202, 16, v203
	v_and_b32_e32 v203, 0xffff0000, v203
	v_pk_fma_f32 v[68:69], v[68:69], v[136:137], v[230:231]
	v_pk_fma_f32 v[70:71], v[70:71], v[138:139], v[232:233]
	v_pk_fma_f32 v[64:65], v[64:65], v[140:141], v[200:201]
	v_pk_fma_f32 v[66:67], v[66:67], v[142:143], v[202:203]
	v_cvt_pk_bf16_f32 v68, v68, v69
	v_cvt_pk_bf16_f32 v69, v70, v71
	v_cvt_pk_bf16_f32 v70, v64, v65
	v_cvt_pk_bf16_f32 v71, v66, v67
	global_store_dwordx4 v239, v[68:71], s[34:35] offset:256
	s_waitcnt vmcnt(15)
	v_lshlrev_b32_e32 v230, 16, v214
	v_and_b32_e32 v231, 0xffff0000, v214
	v_lshlrev_b32_e32 v232, 16, v215
	v_and_b32_e32 v233, 0xffff0000, v215
	v_lshlrev_b32_e32 v214, 16, v216
	v_and_b32_e32 v215, 0xffff0000, v216
	v_lshlrev_b32_e32 v216, 16, v217
	v_and_b32_e32 v217, 0xffff0000, v217
	v_pk_fma_f32 v[60:61], v[60:61], v[128:129], v[230:231]
	v_pk_fma_f32 v[62:63], v[62:63], v[130:131], v[232:233]
	v_pk_fma_f32 v[56:57], v[56:57], v[132:133], v[214:215]
	v_pk_fma_f32 v[58:59], v[58:59], v[134:135], v[216:217]
	v_cvt_pk_bf16_f32 v60, v60, v61
	v_cvt_pk_bf16_f32 v61, v62, v63
	v_cvt_pk_bf16_f32 v62, v56, v57
	v_cvt_pk_bf16_f32 v63, v58, v59
	v_lshl_add_u32 v239, v238, 1, v166
	global_store_dwordx4 v239, v[60:63], s[34:35]
	s_waitcnt vmcnt(15)
	v_lshlrev_b32_e32 v230, 16, v218
	v_and_b32_e32 v231, 0xffff0000, v218
	v_lshlrev_b32_e32 v232, 16, v219
	v_and_b32_e32 v233, 0xffff0000, v219
	v_lshlrev_b32_e32 v218, 16, v220
	v_and_b32_e32 v219, 0xffff0000, v220
	v_lshlrev_b32_e32 v220, 16, v221
	v_and_b32_e32 v221, 0xffff0000, v221
	v_pk_fma_f32 v[52:53], v[52:53], v[136:137], v[230:231]
	v_pk_fma_f32 v[54:55], v[54:55], v[138:139], v[232:233]
	v_pk_fma_f32 v[48:49], v[48:49], v[140:141], v[218:219]
	v_pk_fma_f32 v[50:51], v[50:51], v[142:143], v[220:221]
	v_cvt_pk_bf16_f32 v52, v52, v53
	v_cvt_pk_bf16_f32 v53, v54, v55
	v_cvt_pk_bf16_f32 v54, v48, v49
	v_cvt_pk_bf16_f32 v55, v50, v51
	global_store_dwordx4 v239, v[52:55], s[34:35] offset:256
	s_waitcnt vmcnt(15)
; __device__ __forceinline__ unsigned cvt_pk_bf16(float lo, float hi) { unsigned r; asm("v_cvt_pk_bf16_f32 %0, %1, %2" : "=v"(r) : "v"(lo), "v"(hi)); return r; }
; #define PG8_BAR __builtin_amdgcn_s_barrier()
; template <class Epi, class Sched, bool SWAPD = false>
; __device__ __forceinline__ void gemm_phase(LAS unsigned char* lds, const Gemm g, const Sched& S, const Epi& E) {
;     ...
;         cur = nxt; cA = nA; cB = nB; ++ui;
;         if (wr == 1) PG8_BAR;
;     __device__ __forceinline__ void operator()(const Acc& acc, const Unit& u, int wr, int wc, int fr, int fq) const {
;     ...
;             for (int m = 0; m < 4; ++m) { const size_t off = (size_t)(r0 + ai * 128 + m * 16) * D + col0;
; #pragma unroll
;                 for (int bj = 0; bj < 2; ++bj) { const size_t o2 = off + bj * 128; f32x4 s0, s1;
;                     if (SRC32) { s0 = *(const f32x4*)(sp32 + o2); s1 = *(const f32x4*)(sp32 + o2 + 4); }
;                     else { const u32x4 q = *(const u32x4*)(sp16 + o2); s0 = (f32x4){bf2f(q.x & 0xffffu), bf2f(q.x >> 16), bf2f(q.y & 0xffffu), bf2f(q.y >> 16)}; s1 = (f32x4){bf2f(q.z & 0xffffu), bf2f(q.z >> 16), bf2f(q.w & 0xffffu), bf2f(q.w >> 16)}; }
;                     const f32x4 v0 = s0 + gv[bj][0] * acc[ai][bj][m][0], v1 = s1 + gv[bj][1] * acc[ai][bj][m][1];
;                     if (DST32) { *(f32x4*)(dp32 + o2) = v0; *(f32x4*)(dp32 + o2 + 4) = v1; }
;                     else { u32x4 w; w.x = cvt_pk_bf16(v0.x, v0.y); w.y = cvt_pk_bf16(v0.z, v0.w); w.z = cvt_pk_bf16(v1.x, v1.y); w.w = cvt_pk_bf16(v1.z, v1.w); *(u32x4*)(dp16 + o2) = w; } } }
	v_lshlrev_b32_e32 v230, 16, v222
	v_and_b32_e32 v231, 0xffff0000, v222
	v_lshlrev_b32_e32 v232, 16, v223
	v_and_b32_e32 v233, 0xffff0000, v223
	v_lshlrev_b32_e32 v222, 16, v224
	v_and_b32_e32 v223, 0xffff0000, v224
	v_lshlrev_b32_e32 v224, 16, v225
	v_and_b32_e32 v225, 0xffff0000, v225
	v_pk_fma_f32 v[44:45], v[44:45], v[128:129], v[230:231]
	v_pk_fma_f32 v[46:47], v[46:47], v[130:131], v[232:233]
	v_pk_fma_f32 v[40:41], v[40:41], v[132:133], v[222:223]
	v_pk_fma_f32 v[42:43], v[42:43], v[134:135], v[224:225]
	v_cvt_pk_bf16_f32 v44, v44, v45
	v_cvt_pk_bf16_f32 v45, v46, v47
	v_cvt_pk_bf16_f32 v46, v40, v41
	v_cvt_pk_bf16_f32 v47, v42, v43
	v_lshl_add_u32 v239, v238, 1, v168
	global_store_dwordx4 v239, v[44:47], s[34:35]
	s_waitcnt vmcnt(15)
	v_lshlrev_b32_e32 v230, 16, v226
	v_and_b32_e32 v231, 0xffff0000, v226
	v_lshlrev_b32_e32 v232, 16, v227
	v_and_b32_e32 v233, 0xffff0000, v227
	v_lshlrev_b32_e32 v226, 16, v228
	v_and_b32_e32 v227, 0xffff0000, v228
	v_lshlrev_b32_e32 v228, 16, v229
	v_and_b32_e32 v229, 0xffff0000, v229
	v_pk_fma_f32 v[28:29], v[28:29], v[136:137], v[230:231]
	v_pk_fma_f32 v[30:31], v[30:31], v[138:139], v[232:233]
	v_pk_fma_f32 v[24:25], v[24:25], v[140:141], v[226:227]
	v_pk_fma_f32 v[26:27], v[26:27], v[142:143], v[228:229]
	v_cvt_pk_bf16_f32 v28, v28, v29
	v_cvt_pk_bf16_f32 v29, v30, v31
	v_cvt_pk_bf16_f32 v30, v24, v25
	v_cvt_pk_bf16_f32 v31, v26, v27
	global_store_dwordx4 v239, v[28:31], s[34:35] offset:256
	s_waitcnt vmcnt(11)
	v_lshlrev_b32_e32 v230, 16, v144
	v_and_b32_e32 v231, 0xffff0000, v144
	v_lshlrev_b32_e32 v232, 16, v145
	v_and_b32_e32 v233, 0xffff0000, v145
	v_lshlrev_b32_e32 v144, 16, v146
	v_and_b32_e32 v145, 0xffff0000, v146
	v_lshlrev_b32_e32 v146, 16, v147
	v_and_b32_e32 v147, 0xffff0000, v147
	v_pk_fma_f32 v[36:37], v[36:37], v[128:129], v[230:231]
	v_pk_fma_f32 v[38:39], v[38:39], v[130:131], v[232:233]
	v_pk_fma_f32 v[32:33], v[32:33], v[132:133], v[144:145]
	v_pk_fma_f32 v[34:35], v[34:35], v[134:135], v[146:147]
	v_cvt_pk_bf16_f32 v36, v36, v37
	v_cvt_pk_bf16_f32 v37, v38, v39
	v_cvt_pk_bf16_f32 v38, v32, v33
	v_cvt_pk_bf16_f32 v39, v34, v35
	v_lshl_add_u32 v239, v238, 1, v170
	global_store_dwordx4 v239, v[36:39], s[34:35]
	s_waitcnt vmcnt(11)
	v_lshlrev_b32_e32 v230, 16, v148
	v_and_b32_e32 v231, 0xffff0000, v148
	v_lshlrev_b32_e32 v232, 16, v149
	v_and_b32_e32 v233, 0xffff0000, v149
	v_lshlrev_b32_e32 v148, 16, v150
	v_and_b32_e32 v149, 0xffff0000, v150
	v_lshlrev_b32_e32 v150, 16, v151
	v_and_b32_e32 v151, 0xffff0000, v151
	v_pk_fma_f32 v[12:13], v[12:13], v[136:137], v[230:231]
	v_pk_fma_f32 v[14:15], v[14:15], v[138:139], v[232:233]
	v_pk_fma_f32 v[8:9], v[8:9], v[140:141], v[148:149]
	v_pk_fma_f32 v[10:11], v[10:11], v[142:143], v[150:151]
	v_cvt_pk_bf16_f32 v12, v12, v13
	v_cvt_pk_bf16_f32 v13, v14, v15
	v_cvt_pk_bf16_f32 v14, v8, v9
	v_cvt_pk_bf16_f32 v15, v10, v11
	global_store_dwordx4 v239, v[12:15], s[34:35] offset:256
	s_waitcnt vmcnt(11)
	v_lshlrev_b32_e32 v230, 16, v152
	v_and_b32_e32 v231, 0xffff0000, v152
	v_lshlrev_b32_e32 v232, 16, v153
	v_and_b32_e32 v233, 0xffff0000, v153
	v_lshlrev_b32_e32 v152, 16, v154
	v_and_b32_e32 v153, 0xffff0000, v154
	v_lshlrev_b32_e32 v154, 16, v155
	v_and_b32_e32 v155, 0xffff0000, v155
	v_pk_fma_f32 v[20:21], v[20:21], v[128:129], v[230:231]
	v_pk_fma_f32 v[22:23], v[22:23], v[130:131], v[232:233]
	v_pk_fma_f32 v[16:17], v[16:17], v[132:133], v[152:153]
	v_pk_fma_f32 v[18:19], v[18:19], v[134:135], v[154:155]
	v_cvt_pk_bf16_f32 v20, v20, v21
	v_cvt_pk_bf16_f32 v21, v22, v23
	v_cvt_pk_bf16_f32 v22, v16, v17
	v_cvt_pk_bf16_f32 v23, v18, v19
	v_lshl_add_u32 v239, v238, 1, v172
	global_store_dwordx4 v239, v[20:23], s[34:35]
	s_waitcnt vmcnt(11)
	v_lshlrev_b32_e32 v230, 16, v156
	v_and_b32_e32 v231, 0xffff0000, v156
	v_lshlrev_b32_e32 v232, 16, v157
	v_and_b32_e32 v233, 0xffff0000, v157
	v_lshlrev_b32_e32 v156, 16, v158
	v_and_b32_e32 v157, 0xffff0000, v158
	v_lshlrev_b32_e32 v158, 16, v159
	v_and_b32_e32 v159, 0xffff0000, v159
	v_pk_fma_f32 v[4:5], v[4:5], v[136:137], v[230:231]
	v_pk_fma_f32 v[6:7], v[6:7], v[138:139], v[232:233]
	v_pk_fma_f32 v[0:1], v[0:1], v[140:141], v[156:157]
	v_pk_fma_f32 v[2:3], v[2:3], v[142:143], v[158:159]
	v_cvt_pk_bf16_f32 v4, v4, v5
	v_cvt_pk_bf16_f32 v5, v6, v7
	v_cvt_pk_bf16_f32 v6, v0, v1
	v_cvt_pk_bf16_f32 v7, v2, v3
	global_store_dwordx4 v239, v[4:7], s[34:35] offset:256
	s_andn2_b64 vcc, exec, s[6:7]
	s_mov_b64 s[6:7], -1
	s_cbranch_vccnz .LBB0_1113
	s_andn2_b64 vcc, exec, s[0:1]
	s_cbranch_vccnz .LBB0_1112
	s_barrier
	s_branch .LBB0_1112
